# attention: interior key subtiles skip the per-element band-mask selects (only the two diagonal subtiles per wave need them)
# baseline (speedup 1.0000x reference)
; #define LAS __attribute__((address_space(3)))
; __device__ __forceinline__ void attn_phase(LAS unsigned char* lds, const bf16_t* qkv, bf16_t* og, float* lse, int G, int bid) {
;     const int tid = threadIdx.x, wid = __builtin_amdgcn_readfirstlane(tid >> 6), lane = tid & 63, fr = lane & 15, fq = lane >> 4;
;     LAS unsigned char* Ks = lds; LAS unsigned char* Vs = lds + 256 * KP;
;     const float sl2 = 0.08838834764831845f * 1.4426950408889634f;
;     const int srow = tid >> 4, sch = tid & 15;
;     constexpr int NSEG = 3 * 16 * 16, SEGLEN = 8;
;     for (int seg = bid; seg < NSEG; seg += G) {
;         const int h8 = seg & 7, tq = seg >> 3, sidx = tq & 15, uq = tq >> 4, gb = uq % 3, h = (uq / 3) * 8 + h8;
;         const int sh = 2 * gb, dil = 1 << sh, r = sidx & (dil - 1), blk0 = (sidx >> sh) * SEGLEN;
;         const bf16_t* kbase = qkv + 2048 + h * 128 + sch * 8;
;     ...
;                         const int c = 16 * s + 4 * fq + jj;
;                         const bool valid = (s < 8) ? (c >= a) : (c - 128 <= a);
;                         const float v = valid ? sc[s][jj] * sl2 : -1.0e30f;
.LBB0_1109:
	s_cmp_lt_i32 s84, 14
	s_cselect_b64 s[2:3], -1, 0
	s_add_u32 s48, s82, 0x26680000
	s_addc_u32 s49, s83, 0
	s_and_b64 s[0:1], s[2:3], s[0:1]
	v_writelane_b32 v252, s0, 17
	s_andn2_b64 vcc, exec, s[0:1]
	s_nop 0
	v_writelane_b32 v252, s1, 18
	s_cbranch_vccnz .LBB0_1242
	s_cmpk_gt_i32 s79, 0x2ff
	v_readfirstlane_b32 s16, v224
	s_cbranch_scc1 .LBB0_1242
	s_waitcnt vmcnt(1)
	v_and_b32_e32 v4, 15, v224
	v_lshlrev_b32_e32 v0, 4, v4
	s_waitcnt lgkmcnt(0)
	v_mov_b32_e32 v1, 0
	v_lshl_add_u64 v[2:3], s[82:83], 0, v[0:1]
	s_mov_b64 s[0:1], 0xe681000
	v_bfe_u32 v5, v224, 4, 2
	v_lshl_add_u64 v[132:133], v[2:3], 0, s[0:1]
	s_add_i32 s0, 0, 0x11000
	s_lshr_b32 s1, s16, 2
	s_lshr_b32 s99, s16, 6
	v_add_u32_e32 v150, 0, v0
	v_add_u32_e32 v151, s0, v0
	s_and_b32 s30, s1, 0x3ffffff0
	v_lshlrev_b32_e32 v0, 4, v5
	v_lshlrev_b32_e32 v9, 8, v4
	v_writelane_b32 v252, s48, 19
	v_lshl_add_u64 v[134:135], s[86:87], 0, v[0:1]
	v_add3_u32 v154, v150, v9, v0
	v_mov_b32_e32 v0, 0x80
	s_cmpk_lt_u32 s16, 0x200
	v_writelane_b32 v252, s49, 20
	v_lshlrev_b32_e32 v2, 3, v5
	v_cmp_eq_u32_e64 s[2:3], 0, v5
	v_sub_co_u32_e64 v8, s[62:63], s16, 64
	v_sub_co_u32_e64 v9, s[4:5], s16, v0
	v_mov_b32_e32 v0, 0xc0
	v_mov_b32_e32 v10, 0x100
	v_mov_b32_e32 v11, 0x140
	v_mov_b32_e32 v12, 0x180
	v_mov_b32_e32 v13, 0x1c0
	s_cselect_b64 s[64:65], -1, 0
	s_movk_i32 s28, 0x240
	s_cmpk_lt_u32 s16, 0x240
	v_lshlrev_b32_e32 v5, 2, v5
	v_writelane_b32 v252, s84, 21
	v_sub_co_u32_e64 v0, s[6:7], s16, v0
	v_sub_co_u32_e64 v10, s[8:9], s16, v10
	v_sub_co_u32_e64 v11, s[10:11], s16, v11
	v_sub_co_u32_e64 v12, s[12:13], s16, v12
	v_sub_co_u32_e64 v13, s[14:15], s16, v13
	s_cselect_b64 s[66:67], -1, 0
	s_cmpk_lt_u32 s16, 0x280
	v_cmp_gt_u32_e64 s[16:17], s28, v8
	v_or_b32_e32 v155, s30, v4
	v_or_b32_e32 v8, 1, v5
	v_writelane_b32 v252, s85, 22
	v_cmp_lt_u32_e64 s[30:31], v8, v155
	v_or_b32_e32 v8, 3, v5
	v_cmp_gt_u32_e64 s[24:25], s28, v11
	v_writelane_b32 v252, s30, 23
	v_or_b32_e32 v11, 2, v5
	v_add_u32_e32 v4, 0x80, v155
	v_writelane_b32 v252, s31, 24
	v_cmp_lt_u32_e64 s[30:31], v5, v155
	v_mbcnt_lo_u32_b32 v3, -1, 0
	v_mbcnt_hi_u32_b32 v3, -1, v3
	v_writelane_b32 v252, s30, 25
	v_and_b32_e32 v7, 64, v3
	v_xor_b32_e32 v6, 16, v3
	v_writelane_b32 v252, s31, 26
	v_cmp_lt_u32_e64 s[30:31], v8, v155
	v_or_b32_e32 v8, 17, v5
	v_add_u32_e32 v7, 64, v7
	v_writelane_b32 v252, s30, 27
	v_cmp_lt_i32_e32 vcc, v6, v7
	v_lshrrev_b32_e32 v148, 4, v224
	v_writelane_b32 v252, s31, 28
	v_cmp_lt_u32_e64 s[30:31], v11, v155
	v_or_b32_e32 v11, 16, v5
	v_cndmask_b32_e32 v6, v3, v6, vcc
	v_writelane_b32 v252, s30, 29
	v_lshlrev_b32_e32 v152, 2, v6
	v_xor_b32_e32 v6, 32, v3
	v_writelane_b32 v252, s31, 30
	v_cmp_lt_u32_e64 s[30:31], v8, v155
	v_or_b32_e32 v8, 19, v5
	v_cmp_lt_i32_e32 vcc, v6, v7
	v_writelane_b32 v252, s30, 31
	v_and_b32_e32 v7, 16, v224
	v_cndmask_b32_e32 v3, v3, v6, vcc
	v_writelane_b32 v252, s31, 32
	v_cmp_lt_u32_e64 s[30:31], v11, v155
	v_or_b32_e32 v11, 18, v5
	v_lshlrev_b32_e32 v153, 2, v3
	v_writelane_b32 v252, s30, 33
	v_bfe_u32 v3, v224, 2, 2
	v_lshlrev_b32_e32 v6, 3, v224
	v_writelane_b32 v252, s31, 34
	v_cmp_lt_u32_e64 s[30:31], v8, v155
	v_or_b32_e32 v8, 33, v5
	v_cmp_eq_u32_e32 vcc, 0, v7
	v_writelane_b32 v252, s30, 35
	v_cmp_gt_u32_e64 s[20:21], s28, v0
	v_or_b32_e32 v3, v5, v3
	v_writelane_b32 v252, s31, 36
	v_cmp_lt_u32_e64 s[30:31], v11, v155
	v_or_b32_e32 v11, 32, v5
	v_add_u32_e32 v0, 12, v5
	v_writelane_b32 v252, s30, 37
	v_and_b32_e32 v6, 24, v6
	v_mul_u32_u24_e32 v7, 0x110, v148
	v_writelane_b32 v252, s31, 38
	v_cmp_lt_u32_e64 s[30:31], v8, v155
	v_or_b32_e32 v8, 35, v5
	s_movk_i32 s1, 0x280
	v_writelane_b32 v252, s30, 39
	v_cndmask_b32_e32 v0, v0, v5, vcc
	v_mul_u32_u24_e32 v3, 0x110, v3
	v_writelane_b32 v252, s31, 40
	v_cmp_lt_u32_e64 s[30:31], v11, v155
	v_or_b32_e32 v11, 34, v5
	v_or_b32_e32 v149, 0xffffff80, v148
	v_writelane_b32 v252, s30, 41
	s_cselect_b64 s[68:69], -1, 0
	v_cmp_gt_u32_e64 s[18:19], s28, v9
	v_writelane_b32 v252, s31, 42
	v_cmp_lt_u32_e64 s[30:31], v8, v155
	v_or_b32_e32 v8, 49, v5
	v_cmp_gt_u32_e64 s[22:23], s28, v10
	v_writelane_b32 v252, s30, 43
	v_cmp_gt_u32_e64 s[26:27], s28, v12
	v_cmp_gt_u32_e64 s[28:29], s28, v13
	v_writelane_b32 v252, s31, 44
	v_cmp_lt_u32_e64 s[30:31], v11, v155
	v_or_b32_e32 v11, 48, v5
	v_add3_u32 v156, s0, v3, v6
	v_writelane_b32 v252, s30, 45
	v_cmp_gt_u32_e64 s[92:93], s1, v9
	v_cmp_gt_u32_e64 s[94:95], s1, v10
	v_writelane_b32 v252, s31, 46
	v_cmp_lt_u32_e64 s[30:31], v8, v155
	v_or_b32_e32 v8, 51, v5
	v_cmp_gt_u32_e64 s[96:97], s1, v12
	v_writelane_b32 v252, s30, 47
	s_movk_i32 s71, 0x3000
	v_lshlrev_b32_e32 v136, 1, v2
	v_writelane_b32 v252, s31, 48
	v_cmp_lt_u32_e64 s[30:31], v11, v155
	v_or_b32_e32 v11, 50, v5
	v_lshlrev_b32_e32 v138, 1, v0
	v_writelane_b32 v252, s30, 49
	s_mov_b32 s70, 0x3e0293ee
	v_add_u32_e32 v157, v150, v7
	v_writelane_b32 v252, s31, 50
	v_cmp_lt_u32_e64 s[30:31], v8, v155
	v_or_b32_e32 v8, 0x41, v5
	v_add_u32_e32 v158, v151, v7
	v_writelane_b32 v252, s30, 51
	v_mov_b32_e32 v137, v1
	v_mov_b32_e32 v139, v1
	v_writelane_b32 v252, s31, 52
	v_cmp_lt_u32_e64 s[30:31], v11, v155
	v_or_b32_e32 v11, 64, v5
	v_mov_b32_e32 v159, 0xf149f2ca
	v_writelane_b32 v252, s30, 53
	v_mov_b32_e32 v160, 0x41b17218
	s_mov_b32 s83, 0xff61b1e6
	v_writelane_b32 v252, s31, 54
	v_cmp_lt_u32_e64 s[30:31], v8, v155
	v_or_b32_e32 v8, 0x43, v5
	s_nop 0
	v_writelane_b32 v252, s30, 55
	s_nop 1
	v_writelane_b32 v252, s31, 56
	v_cmp_lt_u32_e64 s[30:31], v11, v155
	v_or_b32_e32 v11, 0x42, v5
	s_nop 0
	v_writelane_b32 v252, s30, 57
	s_nop 1
	v_writelane_b32 v252, s31, 58
	v_cmp_lt_u32_e64 s[30:31], v8, v155
	v_or_b32_e32 v8, 0x51, v5
; __device__ __forceinline__ void attn_phase(LAS unsigned char* lds, const bf16_t* qkv, bf16_t* og, float* lse, int G, int bid) {
;     ...
;                         const int c = 16 * s + 4 * fq + jj;
;                         const bool valid = (s < 8) ? (c >= a) : (c - 128 <= a);
;                         const float v = valid ? sc[s][jj] * sl2 : -1.0e30f;
	s_nop 0
	v_writelane_b32 v252, s30, 59
	s_nop 1
	v_writelane_b32 v252, s31, 60
	v_cmp_lt_u32_e64 s[30:31], v11, v155
	v_or_b32_e32 v11, 0x50, v5
	s_nop 0
	v_writelane_b32 v252, s30, 61
	s_nop 1
	v_writelane_b32 v252, s31, 62
	v_cmp_lt_u32_e64 s[30:31], v8, v155
	v_or_b32_e32 v8, 0x53, v5
	s_nop 0
	v_writelane_b32 v252, s30, 63
	s_nop 1
	v_writelane_b32 v251, s31, 0
	v_cmp_lt_u32_e64 s[30:31], v11, v155
	v_or_b32_e32 v11, 0x52, v5
	s_nop 0
	v_writelane_b32 v251, s30, 1
	s_nop 1
	v_writelane_b32 v251, s31, 2
	v_cmp_lt_u32_e64 s[30:31], v8, v155
	v_or_b32_e32 v8, 0x61, v5
	s_nop 0
	v_writelane_b32 v251, s30, 3
	s_nop 1
	v_writelane_b32 v251, s31, 4
	v_cmp_lt_u32_e64 s[30:31], v11, v155
	v_or_b32_e32 v11, 0x60, v5
	s_nop 0
	v_writelane_b32 v251, s30, 5
	s_nop 1
	v_writelane_b32 v251, s31, 6
	v_cmp_lt_u32_e64 s[30:31], v8, v155
	v_or_b32_e32 v8, 0x63, v5
	s_nop 0
	v_writelane_b32 v251, s30, 7
	s_nop 1
	v_writelane_b32 v251, s31, 8
	v_cmp_lt_u32_e64 s[30:31], v11, v155
	v_or_b32_e32 v11, 0x62, v5
	s_nop 0
	v_writelane_b32 v251, s30, 9
	s_nop 1
	v_writelane_b32 v251, s31, 10
	v_cmp_lt_u32_e64 s[30:31], v8, v155
	v_or_b32_e32 v8, 0x71, v5
	s_nop 0
	v_writelane_b32 v251, s30, 11
	s_nop 1
	v_writelane_b32 v251, s31, 12
	v_cmp_lt_u32_e64 s[30:31], v11, v155
	v_or_b32_e32 v11, 0x70, v5
	s_nop 0
	v_writelane_b32 v251, s30, 13
	s_nop 1
	v_writelane_b32 v251, s31, 14
	v_cmp_lt_u32_e64 s[30:31], v8, v155
	v_or_b32_e32 v8, 0x73, v5
	s_nop 0
	v_writelane_b32 v251, s30, 15
	s_nop 1
	v_writelane_b32 v251, s31, 16
	v_cmp_lt_u32_e64 s[30:31], v11, v155
	v_or_b32_e32 v11, 0x72, v5
	s_nop 0
	v_writelane_b32 v251, s30, 17
	s_nop 1
	v_writelane_b32 v251, s31, 18
	v_cmp_lt_u32_e64 s[30:31], v8, v155
	v_or_b32_e32 v8, 0x81, v5
	s_nop 0
	v_writelane_b32 v251, s30, 19
	s_nop 1
	v_writelane_b32 v251, s31, 20
	v_cmp_lt_u32_e64 s[30:31], v11, v155
	v_or_b32_e32 v11, 0x82, v5
	s_nop 0
	v_writelane_b32 v251, s30, 21
	s_nop 1
	v_writelane_b32 v251, s31, 22
	v_cmp_gt_u32_e64 s[30:31], v5, v155
	s_nop 1
	v_writelane_b32 v251, s30, 23
	s_nop 1
	v_writelane_b32 v251, s31, 24
	v_cmp_gt_u32_e64 s[30:31], v8, v4
	v_or_b32_e32 v8, 0x83, v5
	s_nop 0
	v_writelane_b32 v251, s30, 25
	s_nop 1
	v_writelane_b32 v251, s31, 26
	v_cmp_gt_u32_e64 s[30:31], v8, v4
	v_or_b32_e32 v8, 0x91, v5
	s_nop 0
	v_writelane_b32 v251, s30, 27
	s_nop 1
	v_writelane_b32 v251, s31, 28
	v_cmp_gt_u32_e64 s[30:31], v11, v4
	v_or_b32_e32 v11, 0x90, v5
	s_nop 0
	v_writelane_b32 v251, s30, 29
	s_nop 1
	v_writelane_b32 v251, s31, 30
	v_cmp_gt_u32_e64 s[30:31], v8, v4
	v_or_b32_e32 v8, 0x93, v5
	s_nop 0
	v_writelane_b32 v251, s30, 31
	s_nop 1
	v_writelane_b32 v251, s31, 32
	v_cmp_gt_u32_e64 s[30:31], v11, v4
	v_or_b32_e32 v11, 0x92, v5
	s_nop 0
	v_writelane_b32 v251, s30, 33
	s_nop 1
	v_writelane_b32 v251, s31, 34
	v_cmp_gt_u32_e64 s[30:31], v8, v4
	v_or_b32_e32 v8, 0xa1, v5
	s_nop 0
	v_writelane_b32 v251, s30, 35
	s_nop 1
	v_writelane_b32 v251, s31, 36
	v_cmp_gt_u32_e64 s[30:31], v11, v4
	v_or_b32_e32 v11, 0xa0, v5
	s_nop 0
	v_writelane_b32 v251, s30, 37
	s_nop 1
	v_writelane_b32 v251, s31, 38
	v_cmp_gt_u32_e64 s[30:31], v8, v4
	v_or_b32_e32 v8, 0xa3, v5
	s_nop 0
	v_writelane_b32 v251, s30, 39
	s_nop 1
	v_writelane_b32 v251, s31, 40
	v_cmp_gt_u32_e64 s[30:31], v11, v4
	v_or_b32_e32 v11, 0xa2, v5
	s_nop 0
	v_writelane_b32 v251, s30, 41
	s_nop 1
	v_writelane_b32 v251, s31, 42
	v_cmp_gt_u32_e64 s[30:31], v8, v4
	v_or_b32_e32 v8, 0xb1, v5
	s_nop 0
	v_writelane_b32 v251, s30, 43
	s_nop 1
	v_writelane_b32 v251, s31, 44
	v_cmp_gt_u32_e64 s[30:31], v11, v4
	v_or_b32_e32 v11, 0xb0, v5
	s_nop 0
	v_writelane_b32 v251, s30, 45
	s_nop 1
	v_writelane_b32 v251, s31, 46
	v_cmp_gt_u32_e64 s[30:31], v8, v4
	v_or_b32_e32 v8, 0xb3, v5
	s_nop 0
	v_writelane_b32 v251, s30, 47
	s_nop 1
	v_writelane_b32 v251, s31, 48
	v_cmp_gt_u32_e64 s[30:31], v11, v4
	v_or_b32_e32 v11, 0xb2, v5
	s_nop 0
	v_writelane_b32 v251, s30, 49
	s_nop 1
	v_writelane_b32 v251, s31, 50
	v_cmp_gt_u32_e64 s[30:31], v8, v4
	v_or_b32_e32 v8, 0xc1, v5
	s_nop 0
	v_writelane_b32 v251, s30, 51
	s_nop 1
	v_writelane_b32 v251, s31, 52
	v_cmp_gt_u32_e64 s[30:31], v11, v4
	v_or_b32_e32 v11, 0xc0, v5
	s_nop 0
	v_writelane_b32 v251, s30, 53
	s_nop 1
	v_writelane_b32 v251, s31, 54
	v_cmp_gt_u32_e64 s[30:31], v8, v4
	v_or_b32_e32 v8, 0xc3, v5
	s_nop 0
	v_writelane_b32 v251, s30, 55
	s_nop 1
	v_writelane_b32 v251, s31, 56
	v_cmp_gt_u32_e64 s[30:31], v11, v4
	v_or_b32_e32 v11, 0xc2, v5
	s_nop 0
	v_writelane_b32 v251, s30, 57
	s_nop 1
	v_writelane_b32 v251, s31, 58
	v_cmp_gt_u32_e64 s[30:31], v8, v4
	v_or_b32_e32 v8, 0xd1, v5
	s_nop 0
	v_writelane_b32 v251, s30, 59
	s_nop 1
	v_writelane_b32 v251, s31, 60
	v_cmp_gt_u32_e64 s[30:31], v11, v4
	v_or_b32_e32 v11, 0xd0, v5
	s_nop 0
	v_writelane_b32 v251, s30, 61
	s_nop 1
	v_writelane_b32 v251, s31, 62
	v_cmp_gt_u32_e64 s[30:31], v8, v4
	v_or_b32_e32 v8, 0xd3, v5
	s_nop 0
	v_writelane_b32 v251, s30, 63
	s_nop 1
	v_writelane_b32 v250, s31, 0
	v_cmp_gt_u32_e64 s[30:31], v11, v4
	v_or_b32_e32 v11, 0xd2, v5
	s_nop 0
	v_writelane_b32 v250, s30, 1
	s_nop 1
	v_writelane_b32 v250, s31, 2
	v_cmp_gt_u32_e64 s[30:31], v8, v4
	v_or_b32_e32 v8, 0xe1, v5
	s_nop 0
	v_writelane_b32 v250, s30, 3
	s_nop 1
	v_writelane_b32 v250, s31, 4
	v_cmp_gt_u32_e64 s[30:31], v11, v4
	v_or_b32_e32 v11, 0xe0, v5
	s_nop 0
	v_writelane_b32 v250, s30, 5
	s_nop 1
	v_writelane_b32 v250, s31, 6
	v_cmp_gt_u32_e64 s[30:31], v8, v4
	v_or_b32_e32 v8, 0xe3, v5
	s_nop 0
	v_writelane_b32 v250, s30, 7
	s_nop 1
	v_writelane_b32 v250, s31, 8
	v_cmp_gt_u32_e64 s[30:31], v11, v4
	v_or_b32_e32 v11, 0xe2, v5
	s_nop 0
	v_writelane_b32 v250, s30, 9
	s_nop 1
	v_writelane_b32 v250, s31, 10
	v_cmp_gt_u32_e64 s[30:31], v8, v4
	v_or_b32_e32 v8, 0xf1, v5
	v_cmp_gt_u32_e64 s[84:85], v8, v4
	v_writelane_b32 v250, s30, 11
	v_or_b32_e32 v8, 0xf3, v5
	v_cmp_gt_u32_e64 s[88:89], v8, v4
	v_writelane_b32 v250, s31, 12
	v_cmp_gt_u32_e64 s[30:31], v11, v4
	v_or_b32_e32 v11, 0xf0, v5
	v_or_b32_e32 v5, 0xf2, v5
	v_writelane_b32 v250, s30, 13
	v_cmp_gt_u32_e64 s[90:91], v5, v4
	s_nop 0
	v_writelane_b32 v250, s31, 14
	s_mov_b64 s[30:31], s[86:87]
	v_writelane_b32 v250, s30, 15
	v_cmp_gt_u32_e64 s[86:87], v11, v4
	s_nop 0
	v_writelane_b32 v250, s31, 16
	v_mov_b64_e32 v[140:141], s[30:31]
	v_writelane_b32 v250, s79, 17
	s_branch .LBB0_1113

; __device__ __forceinline__ void attn_phase(LAS unsigned char* lds, const bf16_t* qkv, bf16_t* og, float* lse, int G, int bid) {
;     ...
;             float mx = -3.0e38f;
; #pragma unroll
;             for (int s = 0; s < 16; ++s) {
;                 if (s >= wid && s <= wid + 8 && (s >= 8 || blk > 0)) {
; #pragma unroll
;                     for (int jj = 0; jj < 4; ++jj) {
;                         const int c = 16 * s + 4 * fq + jj;
;                         const bool valid = (s < 8) ? (c >= a) : (c - 128 <= a);
;                         const float v = valid ? sc[s][jj] * sl2 : -1.0e30f;
;                         sc[s][jj] = v; mx = fmaxf(mx, v);
;                     }
;                 }
.LBB0_1191:
	s_cmp_eq_u32 s99, 0
	s_cbranch_scc1 .Lmk_slow_0
	v_pk_mul_f32 v[60:61], v[60:61], s[70:71] op_sel_hi:[1,0]
	v_pk_mul_f32 v[62:63], v[62:63], s[70:71] op_sel_hi:[1,0]
	v_max3_f32 v0, v60, s83, v61
	v_max3_f32 v0, v0, v62, v63
	s_and_b64 vcc, exec, s[36:37]
	s_cbranch_vccnz .LBB0_1157
	s_branch .LBB0_1192

; __device__ __forceinline__ void attn_phase(LAS unsigned char* lds, const bf16_t* qkv, bf16_t* og, float* lse, int G, int bid) {
;     ...
;             float mx = -3.0e38f;
; #pragma unroll
;             for (int s = 0; s < 16; ++s) {
;                 if (s >= wid && s <= wid + 8 && (s >= 8 || blk > 0)) {
; #pragma unroll
;                     for (int jj = 0; jj < 4; ++jj) {
;                         const int c = 16 * s + 4 * fq + jj;
;                         const bool valid = (s < 8) ? (c >= a) : (c - 128 <= a);
;                         const float v = valid ? sc[s][jj] * sl2 : -1.0e30f;
;                         sc[s][jj] = v; mx = fmaxf(mx, v);
;                     }
;                 }
.LBB0_1192:
	s_cmp_eq_u32 s99, 1
	s_cbranch_scc1 .Lmk_slow_1
	v_pk_mul_f32 v[52:53], v[52:53], s[70:71] op_sel_hi:[1,0]
	v_pk_mul_f32 v[54:55], v[54:55], s[70:71] op_sel_hi:[1,0]
	v_max3_f32 v0, v0, v52, v53
	v_max3_f32 v0, v0, v54, v55
	s_and_b64 vcc, exec, s[40:41]
	s_cbranch_vccnz .LBB0_1158
	s_branch .LBB0_1193

; __device__ __forceinline__ void attn_phase(LAS unsigned char* lds, const bf16_t* qkv, bf16_t* og, float* lse, int G, int bid) {
;     ...
;             float mx = -3.0e38f;
; #pragma unroll
;             for (int s = 0; s < 16; ++s) {
;                 if (s >= wid && s <= wid + 8 && (s >= 8 || blk > 0)) {
; #pragma unroll
;                     for (int jj = 0; jj < 4; ++jj) {
;                         const int c = 16 * s + 4 * fq + jj;
;                         const bool valid = (s < 8) ? (c >= a) : (c - 128 <= a);
;                         const float v = valid ? sc[s][jj] * sl2 : -1.0e30f;
;                         sc[s][jj] = v; mx = fmaxf(mx, v);
;                     }
;                 }
.LBB0_1193:
	s_cmp_eq_u32 s99, 2
	s_cbranch_scc1 .Lmk_slow_2
	v_pk_mul_f32 v[72:73], v[72:73], s[70:71] op_sel_hi:[1,0]
	v_pk_mul_f32 v[74:75], v[74:75], s[70:71] op_sel_hi:[1,0]
	v_max3_f32 v0, v0, v72, v73
	v_max3_f32 v0, v0, v74, v75
	s_and_b64 vcc, exec, s[34:35]
	s_cbranch_vccnz .LBB0_1159
	s_branch .LBB0_1194

; __device__ __forceinline__ void attn_phase(LAS unsigned char* lds, const bf16_t* qkv, bf16_t* og, float* lse, int G, int bid) {
;     ...
;             float mx = -3.0e38f;
; #pragma unroll
;             for (int s = 0; s < 16; ++s) {
;                 if (s >= wid && s <= wid + 8 && (s >= 8 || blk > 0)) {
; #pragma unroll
;                     for (int jj = 0; jj < 4; ++jj) {
;                         const int c = 16 * s + 4 * fq + jj;
;                         const bool valid = (s < 8) ? (c >= a) : (c - 128 <= a);
;                         const float v = valid ? sc[s][jj] * sl2 : -1.0e30f;
;                         sc[s][jj] = v; mx = fmaxf(mx, v);
;                     }
;                 }
.LBB0_1194:
	s_cmp_eq_u32 s99, 3
	s_cbranch_scc1 .Lmk_slow_3
	v_pk_mul_f32 v[56:57], v[56:57], s[70:71] op_sel_hi:[1,0]
	v_pk_mul_f32 v[58:59], v[58:59], s[70:71] op_sel_hi:[1,0]
	v_max3_f32 v0, v0, v56, v57
	v_max3_f32 v0, v0, v58, v59
	s_and_b64 vcc, exec, s[42:43]
	s_cbranch_vccnz .LBB0_1160
	s_branch .LBB0_1195

; __device__ __forceinline__ void attn_phase(LAS unsigned char* lds, const bf16_t* qkv, bf16_t* og, float* lse, int G, int bid) {
;     ...
;             float mx = -3.0e38f;
; #pragma unroll
;             for (int s = 0; s < 16; ++s) {
;                 if (s >= wid && s <= wid + 8 && (s >= 8 || blk > 0)) {
; #pragma unroll
;                     for (int jj = 0; jj < 4; ++jj) {
;                         const int c = 16 * s + 4 * fq + jj;
;                         const bool valid = (s < 8) ? (c >= a) : (c - 128 <= a);
;                         const float v = valid ? sc[s][jj] * sl2 : -1.0e30f;
;                         sc[s][jj] = v; mx = fmaxf(mx, v);
;                     }
;                 }
.LBB0_1195:
	s_cmp_eq_u32 s99, 4
	s_cbranch_scc1 .Lmk_slow_4
	v_pk_mul_f32 v[80:81], v[80:81], s[70:71] op_sel_hi:[1,0]
	v_pk_mul_f32 v[82:83], v[82:83], s[70:71] op_sel_hi:[1,0]
	v_max3_f32 v0, v0, v80, v81
	v_max3_f32 v0, v0, v82, v83
	s_and_b64 vcc, exec, s[0:1]
	s_cbranch_vccnz .LBB0_1161
	s_branch .LBB0_1196

; __device__ __forceinline__ void attn_phase(LAS unsigned char* lds, const bf16_t* qkv, bf16_t* og, float* lse, int G, int bid) {
;     ...
;             float mx = -3.0e38f;
; #pragma unroll
;             for (int s = 0; s < 16; ++s) {
;                 if (s >= wid && s <= wid + 8 && (s >= 8 || blk > 0)) {
; #pragma unroll
;                     for (int jj = 0; jj < 4; ++jj) {
;                         const int c = 16 * s + 4 * fq + jj;
;                         const bool valid = (s < 8) ? (c >= a) : (c - 128 <= a);
;                         const float v = valid ? sc[s][jj] * sl2 : -1.0e30f;
;                         sc[s][jj] = v; mx = fmaxf(mx, v);
;                     }
;                 }
.LBB0_1196:
	s_cmp_eq_u32 s99, 5
	s_cbranch_scc1 .Lmk_slow_5
	v_pk_mul_f32 v[64:65], v[64:65], s[70:71] op_sel_hi:[1,0]
	v_pk_mul_f32 v[66:67], v[66:67], s[70:71] op_sel_hi:[1,0]
	v_max3_f32 v0, v0, v64, v65
	v_max3_f32 v0, v0, v66, v67
	s_and_b64 vcc, exec, s[44:45]
	s_cbranch_vccnz .LBB0_1162
	s_branch .LBB0_1197

; __device__ __forceinline__ void attn_phase(LAS unsigned char* lds, const bf16_t* qkv, bf16_t* og, float* lse, int G, int bid) {
;     ...
;             float mx = -3.0e38f;
; #pragma unroll
;             for (int s = 0; s < 16; ++s) {
;                 if (s >= wid && s <= wid + 8 && (s >= 8 || blk > 0)) {
; #pragma unroll
;                     for (int jj = 0; jj < 4; ++jj) {
;                         const int c = 16 * s + 4 * fq + jj;
;                         const bool valid = (s < 8) ? (c >= a) : (c - 128 <= a);
;                         const float v = valid ? sc[s][jj] * sl2 : -1.0e30f;
;                         sc[s][jj] = v; mx = fmaxf(mx, v);
;                     }
;                 }
.LBB0_1197:
	s_cmp_eq_u32 s99, 6
	s_cbranch_scc1 .Lmk_slow_6
	v_pk_mul_f32 v[88:89], v[88:89], s[70:71] op_sel_hi:[1,0]
	v_pk_mul_f32 v[90:91], v[90:91], s[70:71] op_sel_hi:[1,0]
	v_max3_f32 v0, v0, v88, v89
	v_max3_f32 v0, v0, v90, v91
	s_and_b64 vcc, exec, s[30:31]
	s_cbranch_vccnz .LBB0_1163
	s_branch .LBB0_1198

; __device__ __forceinline__ void attn_phase(LAS unsigned char* lds, const bf16_t* qkv, bf16_t* og, float* lse, int G, int bid) {
;     ...
;             float mx = -3.0e38f;
; #pragma unroll
;             for (int s = 0; s < 16; ++s) {
;                 if (s >= wid && s <= wid + 8 && (s >= 8 || blk > 0)) {
; #pragma unroll
;                     for (int jj = 0; jj < 4; ++jj) {
;                         const int c = 16 * s + 4 * fq + jj;
;                         const bool valid = (s < 8) ? (c >= a) : (c - 128 <= a);
;                         const float v = valid ? sc[s][jj] * sl2 : -1.0e30f;
;                         sc[s][jj] = v; mx = fmaxf(mx, v);
;                     }
;                 }
.LBB0_1198:
	s_cmp_eq_u32 s99, 7
	s_cbranch_scc1 .Lmk_slow_7
	v_pk_mul_f32 v[68:69], v[68:69], s[70:71] op_sel_hi:[1,0]
	v_pk_mul_f32 v[70:71], v[70:71], s[70:71] op_sel_hi:[1,0]
	v_max3_f32 v0, v0, v68, v69
	v_max3_f32 v0, v0, v70, v71
	s_and_b64 vcc, exec, s[46:47]
	s_cbranch_vccnz .LBB0_1164
	s_branch .LBB0_1199

; __device__ __forceinline__ void attn_phase(LAS unsigned char* lds, const bf16_t* qkv, bf16_t* og, float* lse, int G, int bid) {
;     ...
;             float mx = -3.0e38f;
; #pragma unroll
;             for (int s = 0; s < 16; ++s) {
;                 if (s >= wid && s <= wid + 8 && (s >= 8 || blk > 0)) {
; #pragma unroll
;                     for (int jj = 0; jj < 4; ++jj) {
;                         const int c = 16 * s + 4 * fq + jj;
;                         const bool valid = (s < 8) ? (c >= a) : (c - 128 <= a);
;                         const float v = valid ? sc[s][jj] * sl2 : -1.0e30f;
;                         sc[s][jj] = v; mx = fmaxf(mx, v);
;                     }
;                 }
.LBB0_1199:
	s_cmp_eq_u32 s99, 0
	s_cbranch_scc1 .Lmk_slow_8
	v_pk_mul_f32 v[96:97], v[96:97], s[70:71] op_sel_hi:[1,0]
	v_pk_mul_f32 v[98:99], v[98:99], s[70:71] op_sel_hi:[1,0]
	v_max3_f32 v0, v0, v96, v97
	v_max3_f32 v0, v0, v98, v99
	s_and_b64 vcc, exec, s[48:49]
	s_cbranch_vccnz .LBB0_1165
	s_branch .LBB0_1200

; __device__ __forceinline__ void attn_phase(LAS unsigned char* lds, const bf16_t* qkv, bf16_t* og, float* lse, int G, int bid) {
;     ...
;             float mx = -3.0e38f;
; #pragma unroll
;             for (int s = 0; s < 16; ++s) {
;                 if (s >= wid && s <= wid + 8 && (s >= 8 || blk > 0)) {
; #pragma unroll
;                     for (int jj = 0; jj < 4; ++jj) {
;                         const int c = 16 * s + 4 * fq + jj;
;                         const bool valid = (s < 8) ? (c >= a) : (c - 128 <= a);
;                         const float v = valid ? sc[s][jj] * sl2 : -1.0e30f;
;                         sc[s][jj] = v; mx = fmaxf(mx, v);
;                     }
;                 }
.LBB0_1200:
	s_cmp_eq_u32 s99, 1
	s_cbranch_scc1 .Lmk_slow_9
	v_pk_mul_f32 v[76:77], v[76:77], s[70:71] op_sel_hi:[1,0]
	v_pk_mul_f32 v[78:79], v[78:79], s[70:71] op_sel_hi:[1,0]
	v_max3_f32 v0, v0, v76, v77
	v_max3_f32 v0, v0, v78, v79
	s_and_b64 vcc, exec, s[50:51]
	s_cbranch_vccnz .LBB0_1166
	s_branch .LBB0_1201

; __device__ __forceinline__ void attn_phase(LAS unsigned char* lds, const bf16_t* qkv, bf16_t* og, float* lse, int G, int bid) {
;     ...
;             float mx = -3.0e38f;
; #pragma unroll
;             for (int s = 0; s < 16; ++s) {
;                 if (s >= wid && s <= wid + 8 && (s >= 8 || blk > 0)) {
; #pragma unroll
;                     for (int jj = 0; jj < 4; ++jj) {
;                         const int c = 16 * s + 4 * fq + jj;
;                         const bool valid = (s < 8) ? (c >= a) : (c - 128 <= a);
;                         const float v = valid ? sc[s][jj] * sl2 : -1.0e30f;
;                         sc[s][jj] = v; mx = fmaxf(mx, v);
;                     }
;                 }
.LBB0_1201:
	s_cmp_eq_u32 s99, 2
	s_cbranch_scc1 .Lmk_slow_10
	v_pk_mul_f32 v[104:105], v[104:105], s[70:71] op_sel_hi:[1,0]
	v_pk_mul_f32 v[106:107], v[106:107], s[70:71] op_sel_hi:[1,0]
	v_max3_f32 v0, v0, v104, v105
	v_max3_f32 v0, v0, v106, v107
	s_and_b64 vcc, exec, s[52:53]
	s_cbranch_vccnz .LBB0_1167
	s_branch .LBB0_1202

; __device__ __forceinline__ void attn_phase(LAS unsigned char* lds, const bf16_t* qkv, bf16_t* og, float* lse, int G, int bid) {
;     ...
;             float mx = -3.0e38f;
; #pragma unroll
;             for (int s = 0; s < 16; ++s) {
;                 if (s >= wid && s <= wid + 8 && (s >= 8 || blk > 0)) {
; #pragma unroll
;                     for (int jj = 0; jj < 4; ++jj) {
;                         const int c = 16 * s + 4 * fq + jj;
;                         const bool valid = (s < 8) ? (c >= a) : (c - 128 <= a);
;                         const float v = valid ? sc[s][jj] * sl2 : -1.0e30f;
;                         sc[s][jj] = v; mx = fmaxf(mx, v);
;                     }
;                 }
.LBB0_1202:
	s_cmp_eq_u32 s99, 3
	s_cbranch_scc1 .Lmk_slow_11
	v_pk_mul_f32 v[84:85], v[84:85], s[70:71] op_sel_hi:[1,0]
	v_pk_mul_f32 v[86:87], v[86:87], s[70:71] op_sel_hi:[1,0]
	v_max3_f32 v0, v0, v84, v85
	v_max3_f32 v0, v0, v86, v87
	s_and_b64 vcc, exec, s[54:55]
	s_cbranch_vccnz .LBB0_1168
	s_branch .LBB0_1203

; __device__ __forceinline__ void attn_phase(LAS unsigned char* lds, const bf16_t* qkv, bf16_t* og, float* lse, int G, int bid) {
;     ...
;             float mx = -3.0e38f;
; #pragma unroll
;             for (int s = 0; s < 16; ++s) {
;                 if (s >= wid && s <= wid + 8 && (s >= 8 || blk > 0)) {
; #pragma unroll
;                     for (int jj = 0; jj < 4; ++jj) {
;                         const int c = 16 * s + 4 * fq + jj;
;                         const bool valid = (s < 8) ? (c >= a) : (c - 128 <= a);
;                         const float v = valid ? sc[s][jj] * sl2 : -1.0e30f;
;                         sc[s][jj] = v; mx = fmaxf(mx, v);
;                     }
;                 }
.LBB0_1203:
	s_cmp_eq_u32 s99, 4
	s_cbranch_scc1 .Lmk_slow_12
	v_pk_mul_f32 v[108:109], v[108:109], s[70:71] op_sel_hi:[1,0]
	v_pk_mul_f32 v[110:111], v[110:111], s[70:71] op_sel_hi:[1,0]
	v_max3_f32 v0, v0, v108, v109
	v_max3_f32 v0, v0, v110, v111
	s_and_b64 vcc, exec, s[56:57]
	s_cbranch_vccnz .LBB0_1169
	s_branch .LBB0_1204

; __device__ __forceinline__ void attn_phase(LAS unsigned char* lds, const bf16_t* qkv, bf16_t* og, float* lse, int G, int bid) {
;     ...
;             float mx = -3.0e38f;
; #pragma unroll
;             for (int s = 0; s < 16; ++s) {
;                 if (s >= wid && s <= wid + 8 && (s >= 8 || blk > 0)) {
; #pragma unroll
;                     for (int jj = 0; jj < 4; ++jj) {
;                         const int c = 16 * s + 4 * fq + jj;
;                         const bool valid = (s < 8) ? (c >= a) : (c - 128 <= a);
;                         const float v = valid ? sc[s][jj] * sl2 : -1.0e30f;
;                         sc[s][jj] = v; mx = fmaxf(mx, v);
;                     }
;                 }
.LBB0_1204:
	s_cmp_eq_u32 s99, 5
	s_cbranch_scc1 .Lmk_slow_13
	v_pk_mul_f32 v[92:93], v[92:93], s[70:71] op_sel_hi:[1,0]
	v_pk_mul_f32 v[94:95], v[94:95], s[70:71] op_sel_hi:[1,0]
	v_max3_f32 v0, v0, v92, v93
	v_max3_f32 v0, v0, v94, v95
	s_and_b64 vcc, exec, s[58:59]
	s_cbranch_vccnz .LBB0_1170
	s_branch .LBB0_1205

; __device__ __forceinline__ void attn_phase(LAS unsigned char* lds, const bf16_t* qkv, bf16_t* og, float* lse, int G, int bid) {
;     ...
;             float mx = -3.0e38f;
; #pragma unroll
;             for (int s = 0; s < 16; ++s) {
;                 if (s >= wid && s <= wid + 8 && (s >= 8 || blk > 0)) {
; #pragma unroll
;                     for (int jj = 0; jj < 4; ++jj) {
;                         const int c = 16 * s + 4 * fq + jj;
;                         const bool valid = (s < 8) ? (c >= a) : (c - 128 <= a);
;                         const float v = valid ? sc[s][jj] * sl2 : -1.0e30f;
;                         sc[s][jj] = v; mx = fmaxf(mx, v);
;                     }
;                 }
.LBB0_1205:
	s_cmp_eq_u32 s99, 6
	s_cbranch_scc1 .Lmk_slow_14
	v_pk_mul_f32 v[112:113], v[112:113], s[70:71] op_sel_hi:[1,0]
	v_pk_mul_f32 v[114:115], v[114:115], s[70:71] op_sel_hi:[1,0]
	v_max3_f32 v0, v0, v112, v113
	v_max3_f32 v0, v0, v114, v115
	s_and_b64 vcc, exec, s[60:61]
	s_cbranch_vccz .LBB0_1171
	s_branch .LBB0_1172
